# grid barrier: XCD leader publishes its generation word without first waiting for its top-level atomic to be acknowledged (the wait only served the acquire that moved to arrival); on top of v82
# speedup vs baseline: 1.0123x; 1.0123x over previous
.LBB0_868:
	s_or_b64 exec, exec, s[6:7]
	v_readlane_b32 s2, v254, 11
	v_readlane_b32 s3, v254, 12
	v_mov_b32_e32 v0, 1
	s_nop 3
	global_atomic_add v141, v0, s[2:3]
	s_waitcnt vmcnt(0)
